# attention softmax: max tree via 16 v_max3 (no self-max), cross-half max via v_permlane32_swap instead of ds_bpermute; restored the MFMA-to-VALU wait state the deleted s_setprio had supplied
# speedup vs baseline: 1.0029x; 1.0029x over previous
; __device__ __forceinline__ void attn_unit(const Params& p, int b, int h, int qb, unsigned char* lds) {
;     ...
;             const unsigned char* Kb = lds + A_KOFF + buf * AK_BYTES + r32 * AK_STRIDE + hi * 16;
;             const unsigned char* Vb = lds + A_VOFF + buf * AV_BYTES + r32 * AV_STRIDE + hi * 16;
;             f32x16 s0, s1;
; #pragma unroll
;             for (int r = 0; r < 16; ++r) { s0[r] = 0.f; s1[r] = 0.f; }
;             const unsigned char* Kb1 = Kb + 32 * AK_STRIDE;
;             bf16x8 ka0 = *(const bf16x8*)(Kb), kb0 = *(const bf16x8*)(Kb1), ka1 = *(const bf16x8*)(Kb + 32), kb1 = *(const bf16x8*)(Kb1 + 32), ka2 = *(const bf16x8*)(Kb + 64), kb2 = *(const bf16x8*)(Kb1 + 64);
;             __builtin_amdgcn_s_setprio(1);
; #pragma unroll
;             for (int d0 = 0; d0 < 12; d0 += 3) {
;                 s0 = __builtin_amdgcn_mfma_f32_32x32x16_bf16(ka0, qf[d0], s0, 0, 0, 0);
;                 s1 = __builtin_amdgcn_mfma_f32_32x32x16_bf16(kb0, qf[d0], s1, 0, 0, 0);
;                 if (d0 + 3 < 12) { ka0 = *(const bf16x8*)(Kb + (d0 + 3) * 32); kb0 = *(const bf16x8*)(Kb1 + (d0 + 3) * 32); }
;                 __builtin_amdgcn_sched_barrier(0);
;                 s0 = __builtin_amdgcn_mfma_f32_32x32x16_bf16(ka1, qf[d0 + 1], s0, 0, 0, 0);
;                 s1 = __builtin_amdgcn_mfma_f32_32x32x16_bf16(kb1, qf[d0 + 1], s1, 0, 0, 0);
;                 if (d0 + 4 < 12) { ka1 = *(const bf16x8*)(Kb + (d0 + 4) * 32); kb1 = *(const bf16x8*)(Kb1 + (d0 + 4) * 32); }
;                 __builtin_amdgcn_sched_barrier(0);
;                 s0 = __builtin_amdgcn_mfma_f32_32x32x16_bf16(ka2, qf[d0 + 2], s0, 0, 0, 0);
;                 s1 = __builtin_amdgcn_mfma_f32_32x32x16_bf16(kb2, qf[d0 + 2], s1, 0, 0, 0);
;                 if (d0 + 5 < 12) { ka2 = *(const bf16x8*)(Kb + (d0 + 5) * 32); kb2 = *(const bf16x8*)(Kb1 + (d0 + 5) * 32); }
;                 __builtin_amdgcn_sched_barrier(0);
;             }
;             __builtin_amdgcn_s_setprio(0);
;             if (kv0 + 63 > q0 + wid * 32) {
; #pragma unroll
;                 for (int r = 0; r < 16; ++r) { const int key = kv0 + 16 * (r >> 3) + 8 * hi + (r & 7);
;                     if (key > qpos) s0[r] = -INFINITY; if (key + 32 > qpos) s1[r] = -INFINITY; }
;             }
.LBB0_500:
	s_mul_i32 s36, s35, 0x6400
	v_add_u32_e32 v225, s36, v219
	ds_read_b128 v[66:69], v225
	ds_read_b128 v[226:229], v225 offset:32
	ds_read_b128 v[82:85], v225 offset:12800
	ds_read_b128 v[230:233], v225 offset:64
	ds_read_b128 v[234:237], v225 offset:12832
	ds_read_b128 v[238:241], v225 offset:12864
	s_waitcnt lgkmcnt(5)
	v_mfma_f32_32x32x16_bf16 v[66:81], v[66:69], v[110:113], 0
	ds_read_b128 v[242:245], v225 offset:96
	ds_read_b128 v[246:249], v225 offset:12896
	s_waitcnt lgkmcnt(5)
	v_mfma_f32_32x32x16_bf16 v[82:97], v[82:85], v[110:113], 0
	v_mfma_f32_32x32x16_bf16 v[66:81], v[226:229], v[114:117], v[66:81]
	ds_read_b128 v[226:229], v225 offset:128
	ds_read_b128 v[250:253], v225 offset:12928
	s_waitcnt lgkmcnt(5)
	v_mfma_f32_32x32x16_bf16 v[82:97], v[234:237], v[114:117], v[82:97]
	v_mfma_f32_32x32x16_bf16 v[66:81], v[230:233], v[118:121], v[66:81]
	ds_read_b128 v[230:233], v225 offset:160
	ds_read_b128 v[234:237], v225 offset:12960
	s_waitcnt lgkmcnt(6)
	v_mfma_f32_32x32x16_bf16 v[82:97], v[238:241], v[118:121], v[82:97]
	s_waitcnt lgkmcnt(5)
	v_mfma_f32_32x32x16_bf16 v[66:81], v[242:245], v[126:129], v[66:81]
	ds_read_b128 v[238:241], v225 offset:192
	ds_read_b128 v[242:245], v225 offset:12992
	s_waitcnt lgkmcnt(6)
	v_mfma_f32_32x32x16_bf16 v[82:97], v[246:249], v[126:129], v[82:97]
	s_waitcnt lgkmcnt(5)
	v_mfma_f32_32x32x16_bf16 v[66:81], v[226:229], v[130:133], v[66:81]
	ds_read_b128 v[226:229], v225 offset:224
	ds_read_b128 v[246:249], v225 offset:13024
	s_waitcnt lgkmcnt(6)
	v_mfma_f32_32x32x16_bf16 v[82:97], v[250:253], v[130:133], v[82:97]
	s_waitcnt lgkmcnt(5)
	v_mfma_f32_32x32x16_bf16 v[66:81], v[230:233], v[138:141], v[66:81]
	ds_read_b128 v[230:233], v225 offset:256
	ds_read_b128 v[250:253], v225 offset:13056
	s_waitcnt lgkmcnt(6)
	v_mfma_f32_32x32x16_bf16 v[82:97], v[234:237], v[138:141], v[82:97]
	s_waitcnt lgkmcnt(5)
	v_mfma_f32_32x32x16_bf16 v[66:81], v[238:241], v[142:145], v[66:81]
	ds_read_b128 v[234:237], v225 offset:288
	ds_read_b128 v[238:241], v225 offset:13088
	s_waitcnt lgkmcnt(6)
	v_mfma_f32_32x32x16_bf16 v[82:97], v[242:245], v[142:145], v[82:97]
	s_waitcnt lgkmcnt(5)
	v_mfma_f32_32x32x16_bf16 v[66:81], v[226:229], v[146:149], v[66:81]
	ds_read_b128 v[226:229], v225 offset:320
	ds_read_b128 v[242:245], v225 offset:13120
	s_waitcnt lgkmcnt(6)
	v_mfma_f32_32x32x16_bf16 v[82:97], v[246:249], v[146:149], v[82:97]
	s_waitcnt lgkmcnt(5)
	v_mfma_f32_32x32x16_bf16 v[66:81], v[230:233], v[150:153], v[66:81]
	ds_read_b128 v[230:233], v225 offset:352
	ds_read_b128 v[246:249], v225 offset:13152
	s_waitcnt lgkmcnt(6)
	v_mfma_f32_32x32x16_bf16 v[82:97], v[250:253], v[150:153], v[82:97]
	s_waitcnt lgkmcnt(5)
	v_mfma_f32_32x32x16_bf16 v[66:81], v[234:237], v[154:157], v[66:81]
	s_waitcnt lgkmcnt(4)
	v_mfma_f32_32x32x16_bf16 v[82:97], v[238:241], v[154:157], v[82:97]
	s_waitcnt lgkmcnt(3)
	v_mfma_f32_32x32x16_bf16 v[66:81], v[226:229], v[158:161], v[66:81]
	s_waitcnt lgkmcnt(2)
	v_mfma_f32_32x32x16_bf16 v[82:97], v[242:245], v[158:161], v[82:97]
	s_waitcnt lgkmcnt(1)
	v_mfma_f32_32x32x16_bf16 v[66:81], v[230:233], v[162:165], v[66:81]
	s_waitcnt lgkmcnt(0)
	v_mfma_f32_32x32x16_bf16 v[82:97], v[246:249], v[162:165], v[82:97]
	s_nop 0
	s_cmp_le_u32 s12, s25
	s_cbranch_scc1 .LBB0_502
	v_add_u32_e32 v225, s12, v178
	v_subrev_u32_e32 v227, 31, v225
	v_subrev_u32_e32 v226, 63, v225
	v_cmp_le_u32_e32 vcc, v227, v187
	s_nop 4
	v_cndmask_b32_e32 v82, v223, v82, vcc
	v_cmp_lt_u32_e32 vcc, v226, v187
	s_nop 1
	v_cndmask_b32_e32 v67, v223, v67, vcc
	v_cmp_le_u32_e32 vcc, v226, v187
	v_subrev_u32_e32 v226, 30, v225
	s_nop 0
	v_cndmask_b32_e32 v66, v223, v66, vcc
	v_cmp_le_u32_e32 vcc, v226, v187
	v_subrev_u32_e32 v226, 61, v225
	s_nop 0
	v_cndmask_b32_e32 v83, v223, v83, vcc
	v_cmp_le_u32_e32 vcc, v226, v187
	v_subrev_u32_e32 v226, 29, v225
	s_nop 0
	v_cndmask_b32_e32 v68, v223, v68, vcc
	v_cmp_le_u32_e32 vcc, v226, v187
	v_subrev_u32_e32 v226, 60, v225
	s_nop 0
	v_cndmask_b32_e32 v84, v223, v84, vcc
	v_cmp_le_u32_e32 vcc, v226, v187
	v_subrev_u32_e32 v226, 28, v225
	s_nop 0
	v_cndmask_b32_e32 v69, v223, v69, vcc
	v_cmp_le_u32_e32 vcc, v226, v187
	v_subrev_u32_e32 v226, 59, v225
	s_nop 0
	v_cndmask_b32_e32 v85, v223, v85, vcc
	v_cmp_le_u32_e32 vcc, v226, v187
	v_subrev_u32_e32 v226, 27, v225
	s_nop 0
	v_cndmask_b32_e32 v70, v223, v70, vcc
	v_cmp_le_u32_e32 vcc, v226, v187
	v_subrev_u32_e32 v226, 58, v225
	s_nop 0
	v_cndmask_b32_e32 v86, v223, v86, vcc
	v_cmp_le_u32_e32 vcc, v226, v187
	v_subrev_u32_e32 v226, 26, v225
	s_nop 0
	v_cndmask_b32_e32 v71, v223, v71, vcc
	v_cmp_le_u32_e32 vcc, v226, v187
	v_subrev_u32_e32 v226, 57, v225
	s_nop 0
	v_cndmask_b32_e32 v87, v223, v87, vcc
	v_cmp_le_u32_e32 vcc, v226, v187
	v_subrev_u32_e32 v226, 25, v225
	s_nop 0
	v_cndmask_b32_e32 v72, v223, v72, vcc
	v_cmp_le_u32_e32 vcc, v226, v187
	v_subrev_u32_e32 v226, 56, v225
	s_nop 0
	v_cndmask_b32_e32 v88, v223, v88, vcc
	v_cmp_le_u32_e32 vcc, v226, v187
	v_subrev_u32_e32 v226, 24, v225
	s_nop 0
	v_cndmask_b32_e32 v73, v223, v73, vcc
	v_cmp_le_u32_e32 vcc, v226, v187
	v_subrev_u32_e32 v226, 47, v225
	s_nop 0
	v_cndmask_b32_e32 v89, v223, v89, vcc
	v_cmp_le_u32_e32 vcc, v226, v187
	v_add_u32_e32 v226, -15, v225
	s_nop 0
	v_cndmask_b32_e32 v74, v223, v74, vcc
	v_cmp_le_u32_e32 vcc, v226, v187
	v_subrev_u32_e32 v226, 46, v225
	s_nop 0
	v_cndmask_b32_e32 v90, v223, v90, vcc
	v_cmp_le_u32_e32 vcc, v226, v187
	v_add_u32_e32 v226, -14, v225
	s_nop 0
	v_cndmask_b32_e32 v75, v223, v75, vcc
	v_cmp_le_u32_e32 vcc, v226, v187
	v_subrev_u32_e32 v226, 45, v225
	s_nop 0
	v_cndmask_b32_e32 v91, v223, v91, vcc
	v_cmp_le_u32_e32 vcc, v226, v187
	v_add_u32_e32 v226, -13, v225
	s_nop 0
	v_cndmask_b32_e32 v76, v223, v76, vcc
	v_cmp_le_u32_e32 vcc, v226, v187
	v_subrev_u32_e32 v226, 44, v225
	s_nop 0
	v_cndmask_b32_e32 v92, v223, v92, vcc
	v_cmp_le_u32_e32 vcc, v226, v187
	v_add_u32_e32 v226, -12, v225
	s_nop 0
	v_cndmask_b32_e32 v77, v223, v77, vcc
	v_cmp_le_u32_e32 vcc, v226, v187
	v_subrev_u32_e32 v226, 43, v225
	s_nop 0
	v_cndmask_b32_e32 v93, v223, v93, vcc
	v_cmp_le_u32_e32 vcc, v226, v187
	v_add_u32_e32 v226, -11, v225
	s_nop 0
	v_cndmask_b32_e32 v78, v223, v78, vcc
	v_cmp_le_u32_e32 vcc, v226, v187
	v_subrev_u32_e32 v226, 42, v225
	s_nop 0
	v_cndmask_b32_e32 v94, v223, v94, vcc
	v_cmp_le_u32_e32 vcc, v226, v187
	v_add_u32_e32 v226, -10, v225
	s_nop 0
	v_cndmask_b32_e32 v79, v223, v79, vcc
	v_cmp_le_u32_e32 vcc, v226, v187
	v_subrev_u32_e32 v226, 41, v225
	s_nop 0
	v_cndmask_b32_e32 v95, v223, v95, vcc
	v_cmp_le_u32_e32 vcc, v226, v187
	v_add_u32_e32 v226, -9, v225
	s_nop 0
	v_cndmask_b32_e32 v80, v223, v80, vcc
	v_cmp_le_u32_e32 vcc, v226, v187
	v_subrev_u32_e32 v226, 40, v225
	v_add_u32_e32 v225, -8, v225
	v_cndmask_b32_e32 v96, v223, v96, vcc
	v_cmp_le_u32_e32 vcc, v226, v187
	s_nop 1
	v_cndmask_b32_e32 v81, v223, v81, vcc
	v_cmp_le_u32_e32 vcc, v225, v187
	s_nop 1
	v_cndmask_b32_e32 v97, v223, v97, vcc
; __device__ __forceinline__ void attn_unit(const Params& p, int b, int h, int qb, unsigned char* lds) {
;     ...
;             float mx = fmaxf(s0[0], s1[0]);
; #pragma unroll
;             for (int r = 1; r < 16; ++r) mx = fmaxf(mx, fmaxf(s0[r], s1[r]));
;             mx = fmaxf(mx, __shfl_xor(mx, 32));
;             if (__any(mx > m_run + 8.f)) {
;                 const float m_new = fmaxf(m_run, mx), alpha = __builtin_amdgcn_exp2f(m_run - m_new); m_run = m_new;
;                 l_run *= alpha;
; #pragma unroll
;                 for (int d = 0; d < 4; ++d)
; #pragma unroll
;                     for (int r = 0; r < 16; ++r) o[d][r] *= alpha;
;             }
.LBB0_502:
	s_nop 8
	v_max3_f32 v225, v66, v67, v68
	v_max3_f32 v226, v69, v70, v71
	v_max3_f32 v227, v72, v73, v74
	v_max3_f32 v228, v75, v76, v77
	v_max3_f32 v225, v225, v78, v79
	v_max3_f32 v226, v226, v80, v81
	v_max3_f32 v227, v227, v82, v83
	v_max3_f32 v228, v228, v84, v85
	v_max3_f32 v225, v225, v86, v87
	v_max3_f32 v226, v226, v88, v89
	v_max3_f32 v227, v227, v90, v91
	v_max3_f32 v228, v228, v92, v93
	v_max3_f32 v225, v225, v94, v95
	v_max3_f32 v226, v226, v96, v97
	v_max3_f32 v225, v225, v226, v227
	v_max_f32_e32 v225, v225, v228
	v_mov_b32_e32 v226, v225
	s_nop 1
	v_permlane32_swap_b32_e32 v225, v226
	v_max_f32_e32 v225, v225, v226
	v_add_f32_e32 v226, 0x41000000, v191
	v_cmp_gt_f32_e32 vcc, v225, v226
	s_cbranch_vccz .LBB0_504
	v_max_f32_e32 v225, v225, v225
	v_max_f32_e32 v226, v191, v191
	v_max_f32_e32 v225, v226, v225
	v_sub_f32_e32 v191, v191, v225
	v_exp_f32_e32 v226, v191
	v_mov_b32_e32 v191, v225
	v_pk_mul_f32 v[64:65], v[64:65], v[226:227] op_sel_hi:[1,0]
	v_pk_mul_f32 v[62:63], v[62:63], v[226:227] op_sel_hi:[1,0]
	v_pk_mul_f32 v[60:61], v[60:61], v[226:227] op_sel_hi:[1,0]
	v_pk_mul_f32 v[58:59], v[58:59], v[226:227] op_sel_hi:[1,0]
	v_pk_mul_f32 v[56:57], v[56:57], v[226:227] op_sel_hi:[1,0]
	v_pk_mul_f32 v[54:55], v[54:55], v[226:227] op_sel_hi:[1,0]
	v_pk_mul_f32 v[52:53], v[52:53], v[226:227] op_sel_hi:[1,0]
	v_pk_mul_f32 v[50:51], v[50:51], v[226:227] op_sel_hi:[1,0]
	v_pk_mul_f32 v[48:49], v[48:49], v[226:227] op_sel_hi:[1,0]
	v_pk_mul_f32 v[46:47], v[46:47], v[226:227] op_sel_hi:[1,0]
	v_pk_mul_f32 v[44:45], v[44:45], v[226:227] op_sel_hi:[1,0]
	v_pk_mul_f32 v[42:43], v[42:43], v[226:227] op_sel_hi:[1,0]
	v_pk_mul_f32 v[40:41], v[40:41], v[226:227] op_sel_hi:[1,0]
	v_pk_mul_f32 v[38:39], v[38:39], v[226:227] op_sel_hi:[1,0]
	v_pk_mul_f32 v[36:37], v[36:37], v[226:227] op_sel_hi:[1,0]
	v_pk_mul_f32 v[34:35], v[34:35], v[226:227] op_sel_hi:[1,0]
	v_pk_mul_f32 v[32:33], v[32:33], v[226:227] op_sel_hi:[1,0]
	v_pk_mul_f32 v[30:31], v[30:31], v[226:227] op_sel_hi:[1,0]
	v_pk_mul_f32 v[28:29], v[28:29], v[226:227] op_sel_hi:[1,0]
	v_pk_mul_f32 v[26:27], v[26:27], v[226:227] op_sel_hi:[1,0]
	v_pk_mul_f32 v[24:25], v[24:25], v[226:227] op_sel_hi:[1,0]
	v_pk_mul_f32 v[22:23], v[22:23], v[226:227] op_sel_hi:[1,0]
	v_pk_mul_f32 v[20:21], v[20:21], v[226:227] op_sel_hi:[1,0]
	v_pk_mul_f32 v[18:19], v[18:19], v[226:227] op_sel_hi:[1,0]
	v_pk_mul_f32 v[16:17], v[16:17], v[226:227] op_sel_hi:[1,0]
	v_pk_mul_f32 v[14:15], v[14:15], v[226:227] op_sel_hi:[1,0]
	v_pk_mul_f32 v[12:13], v[12:13], v[226:227] op_sel_hi:[1,0]
	v_pk_mul_f32 v[10:11], v[10:11], v[226:227] op_sel_hi:[1,0]
	v_pk_mul_f32 v[8:9], v[8:9], v[226:227] op_sel_hi:[1,0]
	v_pk_mul_f32 v[6:7], v[6:7], v[226:227] op_sel_hi:[1,0]
	v_pk_mul_f32 v[4:5], v[4:5], v[226:227] op_sel_hi:[1,0]
	v_pk_mul_f32 v[2:3], v[2:3], v[226:227] op_sel_hi:[1,0]
	v_mul_f32_e32 v189, v189, v226
